# GEMM4 slow-path conv epilogue reads cb rows from an LDS-staged table (idle SA(1,1) buffer) instead of serialized global loads
# speedup vs baseline: 1.0151x; 1.0036x over previous
.LBB0_1183:
	s_mul_i32 s17, s37, 0xfe
	s_add_i32 s17, s17, -2
	s_lshl_b32 s38, s92, 8
	s_and_b64 s[0:1], s[40:41], exec
	s_cselect_b32 s0, s38, 0
	s_lshl_b32 s0, s0, 2
	s_add_i32 s38, s0, 0
	s_and_b32 s0, s17, 0xffe
	s_add_i32 s38, s38, 0x22000
	s_add_i32 s0, s0, -1
	s_cmpk_lt_u32 s0, 0xf00
	s_cselect_b64 s[0:1], -1, 0
	s_add_i32 s37, s37, -1
	s_cmp_lt_u32 s37, 63
	s_cselect_b64 s[60:61], -1, 0
	s_and_b64 s[60:61], s[60:61], s[0:1]
	s_and_b64 s[0:1], s[40:41], s[60:61]
	s_and_b64 vcc, exec, s[0:1]
	s_cbranch_vccnz .LBB0_1189
	v_lshrrev_b32_e32 v166, 6, v218
	v_and_b32_e32 v167, 63, v218
	v_mul_u32_u24_e32 v166, 0x5800, v166
	v_lshl_add_u32 v166, v167, 4, v166
	s_lshl_b32 s0, s72, 10
	v_add_u32_e32 v166, s0, v166
	v_add_u32_e32 v167, 0x2c000, v166
	global_load_dwordx4 v[158:161], v166, s[68:69]
	global_load_dwordx4 v[162:165], v167, s[68:69]
	v_lshlrev_b32_e32 v166, 4, v218
	s_waitcnt vmcnt(1)
	ds_write_b128 v166, v[158:161] offset:49152
	s_waitcnt vmcnt(0)
	ds_write_b128 v166, v[162:165] offset:57344
	v_mov_b32_e32 v54, v218
	s_movk_i32 s0, 0x100
	s_nop 0
	v_cmp_gt_i32_e32 vcc, s0, v54
	s_and_saveexec_b64 s[62:63], vcc
	s_cbranch_execz .LBB0_1188
	v_readlane_b32 s0, v251, 4
	v_add_u32_e32 v55, s17, v54
	v_readlane_b32 s1, v251, 5
	s_andn2_b64 vcc, exec, s[0:1]
	v_med3_i32 v56, v55, 0, v242
	s_cbranch_vccnz .LBB0_1187
	v_lshlrev_b32_e32 v146, 4, v56
	v_lshl_add_u64 v[166:167], v[146:147], 2, s[66:67]
	global_load_dwordx4 v[134:137], v[166:167], off
	global_load_dwordx4 v[158:161], v[166:167], off offset:16
	global_load_dwordx4 v[162:165], v[166:167], off offset:32
	s_nop 0
	global_load_dwordx4 v[166:169], v[166:167], off offset:48
	s_waitcnt vmcnt(0)
	v_pk_add_f32 v[136:137], v[136:137], v[160:161]
	v_pk_add_f32 v[134:135], v[134:135], v[158:159]
	v_pk_add_f32 v[158:159], v[164:165], v[168:169]
	v_pk_add_f32 v[160:161], v[162:163], v[166:167]
	v_pk_add_f32 v[136:137], v[136:137], v[158:159]
	v_pk_add_f32 v[134:135], v[134:135], v[160:161]
	s_nop 0
	v_pk_mov_b32 v[158:159], v[134:135], v[136:137] op_sel:[1,0]
	v_mov_b32_e32 v135, v137
	v_pk_add_f32 v[134:135], v[158:159], v[134:135]
	s_nop 0
	v_add_f32_e32 v57, v134, v135
	v_fmamk_f32 v57, v57, 0x3a800000, v241
	v_rsq_f32_e32 v57, v57
	v_lshl_add_u32 v134, v54, 2, s38
	ds_write_b32 v134, v57

.LBB0_1194:
	v_lshlrev_b32_e32 v248, 2, v148
	v_add_u32_e32 v248, 0xc000, v248
	v_ashrrev_i32_e32 v185, 31, v184
	v_lshlrev_b64 v[114:115], 2, v[184:185]
	v_lshl_add_u64 v[66:67], s[4:5], 0, v[114:115]
	v_lshl_add_u64 v[68:69], s[96:97], 0, v[114:115]
	global_load_dwordx4 v[98:101], v[66:67], off
	global_load_dwordx4 v[102:105], v[68:69], off
	v_or_b32_e32 v68, 0x80, v184
	v_ashrrev_i32_e32 v69, 31, v68
	v_lshl_add_u64 v[66:67], s[78:79], 0, v[114:115]
	v_lshlrev_b64 v[68:69], 2, v[68:69]
	v_lshl_add_u64 v[70:71], s[4:5], 0, v[68:69]
	global_load_dwordx4 v[106:109], v[66:67], off
	global_load_dwordx4 v[80:83], v[70:71], off
	v_lshl_add_u64 v[66:67], s[96:97], 0, v[68:69]
	v_lshl_add_u64 v[68:69], s[78:79], 0, v[68:69]
	global_load_dwordx4 v[90:93], v[66:67], off
	global_load_dwordx4 v[94:97], v[68:69], off
	v_mov_b32_e32 v76, 0
	s_and_b64 vcc, exec, s[60:61]
	v_mov_b32_e32 v84, 0
	v_mov_b32_e32 v85, 0
	v_mov_b32_e32 v86, 0
	v_mov_b32_e32 v87, 0
	v_mov_b32_e32 v66, 0
	v_mov_b32_e32 v67, 0
	v_mov_b32_e32 v68, 0
	v_mov_b32_e32 v69, 0
	s_cbranch_vccnz .LBB0_1196
	ds_read_b128 v[66:69], v221
	ds_read_b128 v[84:87], v222

.LBB0_1198:
	ds_read_b32 v110, v223
	s_waitcnt lgkmcnt(0)
	v_mov_b32_dpp v72, v58 row_shr:1 row_mask:0xf bank_mask:0xf
	v_mov_b32_dpp v73, v59 row_shr:1 row_mask:0xf bank_mask:0xf
	v_mov_b32_dpp v76, v50 row_shr:1 row_mask:0xf bank_mask:0xf
	v_mov_b32_dpp v77, v51 row_shr:1 row_mask:0xf bank_mask:0xf
	v_and_b32_e32 v70, 15, v110
	v_lshl_add_u32 v249, v70, 10, v248
	v_lshlrev_b32_e32 v146, 2, v70
	v_lshl_add_u64 v[70:71], s[68:69], 0, v[146:147]
	v_lshl_add_u64 v[88:89], v[70:71], 0, v[114:115]
	v_and_b32_e32 v71, 16, v110
	v_cmp_eq_u32_e32 vcc, 0, v71
	v_and_b32_e32 v71, 32, v110
	ds_read_b128 v[110:113], v249
	ds_read_b128 v[252:255], v249 offset:512
	v_cmp_eq_u32_e64 s[0:1], 0, v71
	v_cndmask_b32_e64 v116, v66, 0, vcc
	v_cndmask_b32_e64 v117, v67, 0, vcc
	v_cndmask_b32_e64 v118, v68, 0, vcc
	v_cndmask_b32_e64 v119, v69, 0, vcc
	v_cndmask_b32_e64 v84, v84, 0, s[0:1]
	v_cndmask_b32_e64 v85, v85, 0, s[0:1]
	v_cndmask_b32_e64 v86, v86, 0, s[0:1]
	v_cndmask_b32_e64 v87, v87, 0, s[0:1]
	v_cndmask_b32_e64 v76, v76, 0, s[0:1]
	v_cndmask_b32_e64 v77, v77, 0, s[0:1]
	v_mov_b32_dpp v74, v60 row_shr:1 row_mask:0xf bank_mask:0xf
	v_mov_b32_dpp v75, v61 row_shr:1 row_mask:0xf bank_mask:0xf
	v_mov_b32_dpp v78, v52 row_shr:1 row_mask:0xf bank_mask:0xf
	v_mov_b32_dpp v79, v53 row_shr:1 row_mask:0xf bank_mask:0xf
	v_cndmask_b32_e64 v78, v78, 0, s[0:1]
	v_cndmask_b32_e64 v79, v79, 0, s[0:1]
	v_mov_b32_e32 v70, 0
	s_waitcnt vmcnt(0) lgkmcnt(0)
	v_pk_fma_f32 v[112:113], v[212:213], v[108:109], v[112:113]
	v_pk_fma_f32 v[110:111], v[210:211], v[106:107], v[110:111]
	v_pk_fma_f32 v[112:113], v[104:105], v[118:119], v[112:113]
	v_pk_fma_f32 v[110:111], v[102:103], v[116:117], v[110:111]
	v_pk_fma_f32 v[112:113], v[100:101], v[86:87], v[112:113]
	v_pk_fma_f32 v[110:111], v[98:99], v[84:85], v[110:111]
	v_mov_b64_e32 v[84:85], v[252:253]
	v_mov_b64_e32 v[86:87], v[254:255]
	v_mul_f32_e32 v71, 0xbfb8aa3b, v110
	v_exp_f32_e32 v71, v71
	v_cndmask_b32_e64 v88, v72, 0, vcc
	v_cndmask_b32_e64 v89, v73, 0, vcc
	v_cndmask_b32_e64 v116, v74, 0, vcc
	v_add_f32_e32 v71, 1.0, v71
	v_rcp_f32_e32 v71, v71
	v_cndmask_b32_e64 v117, v75, 0, vcc
	v_mul_f32_e32 v71, v110, v71
	s_nop 0
	v_pk_fma_f32 v[84:85], v[214:215], v[94:95], v[84:85]
	s_nop 0
	v_pk_fma_f32 v[84:85], v[90:91], v[88:89], v[84:85]
	v_pk_fma_f32 v[86:87], v[216:217], v[96:97], v[86:87]
	v_pk_fma_f32 v[76:77], v[80:81], v[76:77], v[84:85]
	v_pk_fma_f32 v[86:87], v[92:93], v[116:117], v[86:87]
	v_mul_f32_e32 v71, v76, v71
	v_mul_f32_e32 v76, 0xbfb8aa3b, v111
	v_exp_f32_e32 v76, v76
	v_pk_fma_f32 v[78:79], v[82:83], v[78:79], v[86:87]
	v_add_f32_e32 v76, 1.0, v76
	v_rcp_f32_e32 v76, v76
	s_nop 0
	v_mul_f32_e32 v76, v111, v76
	v_mul_f32_e32 v76, v77, v76
	v_mul_f32_e32 v77, 0xbfb8aa3b, v112
	v_exp_f32_e32 v77, v77
	v_cvt_pk_bf16_f32 v84, v71, v76
	ds_read_b32 v71, v225
	v_add_f32_e32 v77, 1.0, v77
	v_rcp_f32_e32 v77, v77
	s_waitcnt lgkmcnt(0)
	v_and_b32_e32 v76, 15, v71
	v_lshl_add_u32 v249, v76, 10, v248
	v_mul_f32_e32 v77, v112, v77
	v_mul_f32_e32 v77, v78, v77
	v_mul_f32_e32 v78, 0xbfb8aa3b, v113
	v_exp_f32_e32 v78, v78
	v_lshlrev_b32_e32 v146, 2, v76
	v_add_f32_e32 v78, 1.0, v78
	v_rcp_f32_e32 v78, v78
	s_nop 0
	v_mul_f32_e32 v78, v113, v78
	v_mul_f32_e32 v78, v79, v78
	v_cvt_pk_bf16_f32 v85, v77, v78
	v_lshl_add_u64 v[76:77], s[68:69], 0, v[146:147]
	v_lshl_add_u64 v[86:87], v[76:77], 0, v[114:115]
	v_and_b32_e32 v76, 16, v71
	v_cmp_eq_u32_e32 vcc, 0, v76
	ds_read_b128 v[76:79], v249
	ds_read_b128 v[252:255], v249 offset:512
	v_and_b32_e32 v71, 32, v71
	v_cmp_eq_u32_e64 s[0:1], 0, v71
	v_cndmask_b32_e64 v88, v210, 0, vcc
	v_cndmask_b32_e64 v89, v211, 0, vcc
	v_cndmask_b32_e64 v110, v212, 0, vcc
	v_cndmask_b32_e64 v111, v213, 0, vcc
	v_cndmask_b32_e64 v66, v66, 0, s[0:1]
	v_cndmask_b32_e64 v67, v67, 0, s[0:1]
	v_cndmask_b32_e64 v68, v68, 0, s[0:1]
	v_cndmask_b32_e64 v69, v69, 0, s[0:1]
	v_cndmask_b32_e64 v72, v72, 0, s[0:1]
	v_cndmask_b32_e64 v73, v73, 0, s[0:1]
	v_cndmask_b32_e64 v74, v74, 0, s[0:1]
	v_cndmask_b32_e64 v75, v75, 0, s[0:1]
	s_waitcnt lgkmcnt(0)
	v_pk_fma_f32 v[78:79], v[204:205], v[108:109], v[78:79]
	v_pk_fma_f32 v[76:77], v[202:203], v[106:107], v[76:77]
	v_pk_fma_f32 v[78:79], v[104:105], v[110:111], v[78:79]
	v_pk_fma_f32 v[76:77], v[102:103], v[88:89], v[76:77]
	v_pk_fma_f32 v[78:79], v[100:101], v[68:69], v[78:79]
	v_pk_fma_f32 v[76:77], v[98:99], v[66:67], v[76:77]
	v_mov_b64_e32 v[66:67], v[252:253]
	v_mov_b64_e32 v[68:69], v[254:255]
	v_mul_f32_e32 v71, 0xbfb8aa3b, v76
	v_exp_f32_e32 v71, v71
	v_cndmask_b32_e64 v86, v214, 0, vcc
	v_cndmask_b32_e64 v87, v215, 0, vcc
	v_cndmask_b32_e64 v88, v216, 0, vcc
	v_add_f32_e32 v71, 1.0, v71
	v_rcp_f32_e32 v71, v71
	v_cndmask_b32_e64 v89, v217, 0, vcc
	v_mul_f32_e32 v71, v76, v71
	s_nop 0
	v_pk_fma_f32 v[66:67], v[206:207], v[94:95], v[66:67]
	s_nop 0
	v_pk_fma_f32 v[66:67], v[90:91], v[86:87], v[66:67]
	v_pk_fma_f32 v[68:69], v[208:209], v[96:97], v[68:69]
	v_pk_fma_f32 v[66:67], v[80:81], v[72:73], v[66:67]
	v_pk_fma_f32 v[68:69], v[92:93], v[88:89], v[68:69]
	v_mul_f32_e32 v66, v66, v71
	v_mul_f32_e32 v71, 0xbfb8aa3b, v77
	v_exp_f32_e32 v71, v71
	v_pk_fma_f32 v[68:69], v[82:83], v[74:75], v[68:69]
	v_add_f32_e32 v71, 1.0, v71
	v_rcp_f32_e32 v71, v71
	s_nop 0
	v_mul_f32_e32 v71, v77, v71
	v_mul_f32_e32 v67, v67, v71
	v_mul_f32_e32 v71, 0xbfb8aa3b, v78
	v_exp_f32_e32 v71, v71
	v_cvt_pk_bf16_f32 v74, v66, v67
	s_nop 0
	v_add_f32_e32 v71, 1.0, v71
	v_rcp_f32_e32 v71, v71
	s_nop 0
	v_mul_f32_e32 v71, v78, v71
	v_mul_f32_e32 v68, v68, v71
	v_mul_f32_e32 v71, 0xbfb8aa3b, v79
	v_exp_f32_e32 v71, v71
	s_nop 0
	v_add_f32_e32 v71, 1.0, v71
	v_rcp_f32_e32 v71, v71
	s_nop 0
	v_mul_f32_e32 v71, v79, v71
	v_mul_f32_e32 v69, v69, v71
	v_cvt_pk_bf16_f32 v75, v68, v69
	ds_read_b32 v68, v227
	s_waitcnt lgkmcnt(0)
	v_and_b32_e32 v66, 15, v68
	v_lshl_add_u32 v249, v66, 10, v248
	v_lshlrev_b32_e32 v146, 2, v66
	v_lshl_add_u64 v[66:67], s[68:69], 0, v[146:147]
	v_lshl_add_u64 v[72:73], v[66:67], 0, v[114:115]
	v_and_b32_e32 v66, 16, v68
	v_cmp_eq_u32_e32 vcc, 0, v66
	v_and_b32_e32 v66, 32, v68
	v_cmp_eq_u32_e64 s[0:1], 0, v66
	ds_read_b128 v[66:69], v249
	ds_read_b128 v[252:255], v249 offset:512
	v_cndmask_b32_e64 v76, v202, 0, vcc
	v_cndmask_b32_e64 v77, v203, 0, vcc
	v_cndmask_b32_e64 v86, v204, 0, vcc
	v_cndmask_b32_e64 v87, v205, 0, vcc
	v_cndmask_b32_e64 v78, v210, 0, s[0:1]
	v_cndmask_b32_e64 v79, v211, 0, s[0:1]
	v_cndmask_b32_e64 v88, v212, 0, s[0:1]
	v_cndmask_b32_e64 v89, v213, 0, s[0:1]
	v_cndmask_b32_e64 v110, v216, 0, s[0:1]
	v_cndmask_b32_e64 v111, v217, 0, s[0:1]
	s_waitcnt lgkmcnt(0)
	v_pk_fma_f32 v[68:69], v[56:57], v[108:109], v[68:69]
	v_pk_fma_f32 v[66:67], v[54:55], v[106:107], v[66:67]
	v_pk_fma_f32 v[68:69], v[104:105], v[86:87], v[68:69]
	v_pk_fma_f32 v[66:67], v[102:103], v[76:77], v[66:67]
	v_pk_fma_f32 v[76:77], v[100:101], v[88:89], v[68:69]
	v_pk_fma_f32 v[78:79], v[98:99], v[78:79], v[66:67]
	v_mov_b64_e32 v[66:67], v[252:253]
	v_mov_b64_e32 v[68:69], v[254:255]
	v_mul_f32_e32 v71, 0xbfb8aa3b, v78
	v_exp_f32_e32 v71, v71
	v_cndmask_b32_e64 v72, v206, 0, vcc
	v_cndmask_b32_e64 v73, v207, 0, vcc
	v_cndmask_b32_e64 v86, v214, 0, s[0:1]
	v_add_f32_e32 v71, 1.0, v71
	v_rcp_f32_e32 v71, v71
	v_cndmask_b32_e64 v87, v215, 0, s[0:1]
	v_cndmask_b32_e64 v88, v208, 0, vcc
	v_cndmask_b32_e64 v89, v209, 0, vcc
	v_mul_f32_e32 v71, v78, v71
	s_nop 0
	v_pk_fma_f32 v[66:67], v[50:51], v[94:95], v[66:67]
	s_nop 0
	v_pk_fma_f32 v[66:67], v[90:91], v[72:73], v[66:67]
	v_pk_fma_f32 v[68:69], v[52:53], v[96:97], v[68:69]
	v_pk_fma_f32 v[66:67], v[80:81], v[86:87], v[66:67]
	v_pk_fma_f32 v[68:69], v[92:93], v[88:89], v[68:69]
	v_mul_f32_e32 v66, v66, v71
	v_mul_f32_e32 v71, 0xbfb8aa3b, v79
	v_exp_f32_e32 v71, v71
	v_pk_fma_f32 v[68:69], v[82:83], v[110:111], v[68:69]
	v_add_f32_e32 v71, 1.0, v71
	v_rcp_f32_e32 v71, v71
	s_nop 0
	v_mul_f32_e32 v71, v79, v71
	v_mul_f32_e32 v67, v67, v71
	v_mul_f32_e32 v71, 0xbfb8aa3b, v76
	v_exp_f32_e32 v71, v71
	s_nop 0
	v_add_f32_e32 v71, 1.0, v71
	v_rcp_f32_e32 v71, v71
	s_nop 0
	v_mul_f32_e32 v71, v76, v71
	v_mul_f32_e32 v71, v68, v71
	v_mul_f32_e32 v68, 0xbfb8aa3b, v77
	v_exp_f32_e32 v68, v68
	s_nop 0
	v_add_f32_e32 v68, 1.0, v68
	v_rcp_f32_e32 v68, v68
	s_nop 0
	v_mul_f32_e32 v68, v77, v68
	v_mul_f32_e32 v69, v69, v68
	v_cvt_pk_bf16_f32 v69, v71, v69
	ds_read_b32 v71, v229
	v_cvt_pk_bf16_f32 v68, v66, v67
	s_waitcnt lgkmcnt(0)
	v_and_b32_e32 v66, 15, v71
	v_lshl_add_u32 v249, v66, 10, v248
	v_lshlrev_b32_e32 v146, 2, v66
	v_lshl_add_u64 v[66:67], s[68:69], 0, v[146:147]
	v_lshl_add_u64 v[86:87], v[66:67], 0, v[114:115]
	ds_read_b128 v[76:79], v249
	ds_read_b128 v[252:255], v249 offset:512
	v_and_b32_e32 v66, 16, v71
	v_cmp_eq_u32_e32 vcc, 0, v66
	v_and_b32_e32 v66, 32, v71
	v_cmp_eq_u32_e64 s[62:63], 0, v66
	v_cndmask_b32_e64 v66, v54, 0, vcc
	v_cndmask_b32_e64 v67, v55, 0, vcc
	v_cndmask_b32_e64 v72, v202, 0, s[62:63]
	v_cndmask_b32_e64 v73, v203, 0, s[62:63]
	v_cndmask_b32_e64 v88, v56, 0, vcc
	v_cndmask_b32_e64 v89, v57, 0, vcc
	v_cndmask_b32_e64 v110, v204, 0, s[62:63]
	v_cndmask_b32_e64 v111, v205, 0, s[62:63]
	v_cndmask_b32_e64 v112, v208, 0, s[62:63]
	v_cndmask_b32_e64 v113, v209, 0, s[62:63]
	s_waitcnt lgkmcnt(0)
	v_pk_fma_f32 v[76:77], v[62:63], v[106:107], v[76:77]
	v_pk_fma_f32 v[78:79], v[64:65], v[108:109], v[78:79]
	v_pk_fma_f32 v[76:77], v[102:103], v[66:67], v[76:77]
	v_pk_fma_f32 v[66:67], v[104:105], v[88:89], v[78:79]
	v_pk_fma_f32 v[72:73], v[98:99], v[72:73], v[76:77]
	v_mov_b64_e32 v[76:77], v[252:253]
	v_mov_b64_e32 v[78:79], v[254:255]
	v_mul_f32_e32 v71, 0xbfb8aa3b, v72
	v_exp_f32_e32 v71, v71
	v_pk_fma_f32 v[66:67], v[100:101], v[110:111], v[66:67]
	v_cndmask_b32_e64 v110, v52, 0, vcc
	v_cndmask_b32_e64 v111, v53, 0, vcc
	v_add_f32_e32 v71, 1.0, v71
	v_rcp_f32_e32 v71, v71
	v_cndmask_b32_e64 v86, v50, 0, vcc
	v_cndmask_b32_e64 v87, v51, 0, vcc
	v_cndmask_b32_e64 v88, v206, 0, s[62:63]
	v_mul_f32_e32 v71, v72, v71
	v_mul_f32_e32 v72, 0xbfb8aa3b, v73
	v_exp_f32_e32 v72, v72
	v_cndmask_b32_e64 v89, v207, 0, s[62:63]
	s_andn2_b64 vcc, exec, s[12:13]
	v_add_f32_e32 v72, 1.0, v72
	v_rcp_f32_e32 v72, v72
	s_nop 0
	v_pk_fma_f32 v[78:79], v[60:61], v[96:97], v[78:79]
	v_mul_f32_e32 v72, v73, v72
	v_mul_f32_e32 v73, 0xbfb8aa3b, v66
	v_exp_f32_e32 v73, v73
	v_pk_fma_f32 v[78:79], v[92:93], v[110:111], v[78:79]
	v_pk_fma_f32 v[76:77], v[58:59], v[94:95], v[76:77]
	v_pk_fma_f32 v[78:79], v[82:83], v[112:113], v[78:79]
	v_add_f32_e32 v73, 1.0, v73
	v_rcp_f32_e32 v73, v73
	v_pk_fma_f32 v[76:77], v[90:91], v[86:87], v[76:77]
	v_mov_b32_e32 v110, 0
	v_pk_fma_f32 v[76:77], v[80:81], v[88:89], v[76:77]
	v_mul_f32_e32 v66, v66, v73
	v_mul_f32_e32 v73, 0xbfb8aa3b, v67
	v_exp_f32_e32 v73, v73
	v_mul_f32_e32 v66, v78, v66
	v_mul_f32_e32 v71, v76, v71
	v_mul_f32_e32 v72, v77, v72
	v_add_f32_e32 v73, 1.0, v73
	v_rcp_f32_e32 v73, v73
	v_mov_b32_e32 v76, 0
	v_mov_b32_e32 v77, 0
	v_mov_b32_e32 v78, 0
	v_mul_f32_e32 v67, v67, v73
	v_mul_f32_e32 v67, v79, v67
	v_cvt_pk_bf16_f32 v89, v66, v67
	v_cndmask_b32_e64 v66, 0, 1, s[12:13]
	v_cmp_ne_u32_e64 s[62:63], 1, v66
	v_mov_b32_e32 v79, 0
	v_mov_b32_e32 v111, 0
	v_mov_b32_e32 v112, 0
	v_mov_b32_e32 v113, 0
	v_cvt_pk_bf16_f32 v88, v71, v72
	s_cbranch_vccnz .LBB0_1200
	ds_read_b128 v[110:113], v219 offset:3072
	ds_read_b128 v[76:79], v219 offset:2048

.LBB0_1202:
	ds_read_b32 v86, v231
	s_waitcnt lgkmcnt(2)
	v_mov_b32_dpp v118, v46 row_shr:1 row_mask:0xf bank_mask:0xf
	v_mov_b32_dpp v119, v47 row_shr:1 row_mask:0xf bank_mask:0xf
	s_waitcnt lgkmcnt(1)
	v_mov_b32_dpp v70, v38 row_shr:1 row_mask:0xf bank_mask:0xf
	v_mov_b32_dpp v71, v39 row_shr:1 row_mask:0xf bank_mask:0xf
	s_waitcnt lgkmcnt(0)
	v_and_b32_e32 v66, 15, v86
	v_lshl_add_u32 v249, v66, 10, v248
	v_lshlrev_b32_e32 v146, 2, v66
	v_lshl_add_u64 v[66:67], s[68:69], 0, v[146:147]
	v_lshl_add_u64 v[66:67], v[66:67], 0, v[114:115]
	ds_read_b128 v[122:125], v249
	ds_read_b128 v[252:255], v249 offset:512
	v_and_b32_e32 v87, 16, v86
	v_cmp_eq_u32_e32 vcc, 0, v87
	v_and_b32_e32 v86, 32, v86
	v_cmp_eq_u32_e64 s[0:1], 0, v86
	v_cndmask_b32_e64 v86, v110, 0, vcc
	v_cndmask_b32_e64 v87, v111, 0, vcc
	v_cndmask_b32_e64 v126, v112, 0, vcc
	v_cndmask_b32_e64 v127, v113, 0, vcc
	v_cndmask_b32_e64 v76, v76, 0, s[0:1]
	v_cndmask_b32_e64 v77, v77, 0, s[0:1]
	v_cndmask_b32_e64 v78, v78, 0, s[0:1]
	v_cndmask_b32_e64 v79, v79, 0, s[0:1]
	v_cndmask_b32_e64 v70, v70, 0, s[0:1]
	v_cndmask_b32_e64 v71, v71, 0, s[0:1]
	v_mov_b32_dpp v120, v48 row_shr:1 row_mask:0xf bank_mask:0xf
	v_mov_b32_dpp v121, v49 row_shr:1 row_mask:0xf bank_mask:0xf
	v_mov_b32_dpp v72, v40 row_shr:1 row_mask:0xf bank_mask:0xf
	v_mov_b32_dpp v73, v41 row_shr:1 row_mask:0xf bank_mask:0xf
	v_cndmask_b32_e64 v72, v72, 0, s[0:1]
	v_cndmask_b32_e64 v73, v73, 0, s[0:1]
	v_mov_b32_e32 v116, 0
	v_mov_b32_e32 v128, 0
	v_mov_b32_e32 v129, 0
	v_mov_b32_e32 v130, 0
	v_mov_b32_e32 v131, 0
	s_waitcnt lgkmcnt(0)
	v_pk_fma_f32 v[124:125], v[196:197], v[108:109], v[124:125]
	v_pk_fma_f32 v[122:123], v[194:195], v[106:107], v[122:123]
	s_nop 0
	v_pk_fma_f32 v[86:87], v[102:103], v[86:87], v[122:123]
	v_pk_fma_f32 v[122:123], v[104:105], v[126:127], v[124:125]
	v_pk_fma_f32 v[86:87], v[98:99], v[76:77], v[86:87]
	v_pk_fma_f32 v[122:123], v[100:101], v[78:79], v[122:123]
	v_mov_b64_e32 v[76:77], v[252:253]
	v_mov_b64_e32 v[78:79], v[254:255]
	v_cndmask_b32_e64 v66, v118, 0, vcc
	v_cndmask_b32_e64 v67, v119, 0, vcc
	v_cndmask_b32_e64 v124, v120, 0, vcc
	v_cndmask_b32_e64 v125, v121, 0, vcc
	v_mov_b32_e32 v126, 0
	v_mov_b32_e32 v127, 0
	s_nop 0
	v_pk_fma_f32 v[76:77], v[198:199], v[94:95], v[76:77]
	s_nop 0
	v_pk_fma_f32 v[66:67], v[90:91], v[66:67], v[76:77]
	v_pk_fma_f32 v[78:79], v[200:201], v[96:97], v[78:79]
	v_pk_fma_f32 v[66:67], v[80:81], v[70:71], v[66:67]
	v_mul_f32_e32 v70, 0xbfb8aa3b, v86
	v_exp_f32_e32 v70, v70
	v_mul_f32_e32 v71, 0xbfb8aa3b, v123
	v_exp_f32_e32 v71, v71
	v_pk_fma_f32 v[78:79], v[92:93], v[124:125], v[78:79]
	v_add_f32_e32 v70, 1.0, v70
	v_rcp_f32_e32 v70, v70
	v_add_f32_e32 v71, 1.0, v71
	v_rcp_f32_e32 v71, v71
	v_pk_fma_f32 v[72:73], v[82:83], v[72:73], v[78:79]
	v_mul_f32_e32 v70, v86, v70
	v_mul_f32_e32 v66, v66, v70
	v_mul_f32_e32 v70, 0xbfb8aa3b, v87
	v_exp_f32_e32 v70, v70
	v_mul_f32_e32 v71, v123, v71
	v_mul_f32_e32 v71, v73, v71
	v_mov_b32_e32 v124, 0
	v_add_f32_e32 v70, 1.0, v70
	v_rcp_f32_e32 v70, v70
	v_mov_b32_e32 v125, 0
	v_mul_f32_e32 v70, v87, v70
	v_mul_f32_e32 v67, v67, v70
	v_mul_f32_e32 v70, 0xbfb8aa3b, v122
	v_exp_f32_e32 v70, v70
	v_cvt_pk_bf16_f32 v78, v66, v67
	s_nop 0
	v_add_f32_e32 v70, 1.0, v70
	v_rcp_f32_e32 v70, v70
	s_nop 0
	v_mul_f32_e32 v70, v122, v70
	v_mul_f32_e32 v70, v72, v70
	v_cvt_pk_bf16_f32 v79, v70, v71
	ds_read_b32 v70, v233
	s_waitcnt lgkmcnt(0)
	v_and_b32_e32 v66, 15, v70
	v_lshl_add_u32 v249, v66, 10, v248
	v_lshlrev_b32_e32 v146, 2, v66
	v_lshl_add_u64 v[66:67], s[68:69], 0, v[146:147]
	v_lshl_add_u64 v[66:67], v[66:67], 0, v[114:115]
	v_and_b32_e32 v71, 16, v70
	v_and_b32_e32 v70, 32, v70
	v_cmp_eq_u32_e32 vcc, 0, v71
	v_cmp_eq_u32_e64 s[0:1], 0, v70
	ds_read_b128 v[70:73], v249
	ds_read_b128 v[252:255], v249 offset:512
	v_cndmask_b32_e64 v76, v194, 0, vcc
	v_cndmask_b32_e64 v86, v110, 0, s[0:1]
	v_cndmask_b32_e64 v77, v195, 0, vcc
	v_cndmask_b32_e64 v87, v111, 0, s[0:1]
	v_cndmask_b32_e64 v110, v196, 0, vcc
	v_cndmask_b32_e64 v111, v197, 0, vcc
	v_cndmask_b32_e64 v112, v112, 0, s[0:1]
	v_cndmask_b32_e64 v113, v113, 0, s[0:1]
	s_waitcnt lgkmcnt(0)
	v_pk_fma_f32 v[72:73], v[188:189], v[108:109], v[72:73]
	v_pk_fma_f32 v[70:71], v[186:187], v[106:107], v[70:71]
	v_pk_fma_f32 v[72:73], v[104:105], v[110:111], v[72:73]
	v_pk_fma_f32 v[70:71], v[102:103], v[76:77], v[70:71]
	v_pk_fma_f32 v[76:77], v[100:101], v[112:113], v[72:73]
	v_pk_fma_f32 v[86:87], v[98:99], v[86:87], v[70:71]
	v_mov_b64_e32 v[70:71], v[252:253]
	v_mov_b64_e32 v[72:73], v[254:255]
	v_cndmask_b32_e64 v66, v198, 0, vcc
	v_cndmask_b32_e64 v67, v199, 0, vcc
	v_cndmask_b32_e64 v112, v200, 0, vcc
	v_cndmask_b32_e64 v113, v201, 0, vcc
	v_cndmask_b32_e64 v110, v118, 0, s[0:1]
	v_cndmask_b32_e64 v111, v119, 0, s[0:1]
	v_cndmask_b32_e64 v118, v120, 0, s[0:1]
	v_cndmask_b32_e64 v119, v121, 0, s[0:1]
	s_nop 0
	v_pk_fma_f32 v[72:73], v[192:193], v[96:97], v[72:73]
	v_pk_fma_f32 v[70:71], v[190:191], v[94:95], v[70:71]
	s_nop 0
	v_pk_fma_f32 v[66:67], v[90:91], v[66:67], v[70:71]
	v_pk_fma_f32 v[70:71], v[92:93], v[112:113], v[72:73]
	v_mul_f32_e32 v72, 0xbfb8aa3b, v86
	v_exp_f32_e32 v72, v72
	v_pk_fma_f32 v[66:67], v[80:81], v[110:111], v[66:67]
	v_pk_fma_f32 v[70:71], v[82:83], v[118:119], v[70:71]
	v_add_f32_e32 v72, 1.0, v72
	v_rcp_f32_e32 v72, v72
	s_nop 0
	v_mul_f32_e32 v72, v86, v72
	v_mul_f32_e32 v66, v66, v72
	v_mul_f32_e32 v72, 0xbfb8aa3b, v87
	v_exp_f32_e32 v72, v72
	s_nop 0
	v_add_f32_e32 v72, 1.0, v72
	v_rcp_f32_e32 v72, v72
	s_nop 0
	v_mul_f32_e32 v72, v87, v72
	v_mul_f32_e32 v67, v67, v72
	v_mul_f32_e32 v72, 0xbfb8aa3b, v76
	v_exp_f32_e32 v72, v72
	s_nop 0
	v_add_f32_e32 v72, 1.0, v72
	v_rcp_f32_e32 v72, v72
	s_nop 0
	v_mul_f32_e32 v72, v76, v72
	v_mul_f32_e32 v70, v70, v72
	v_mul_f32_e32 v72, 0xbfb8aa3b, v77
	v_exp_f32_e32 v72, v72
	s_nop 0
	v_add_f32_e32 v72, 1.0, v72
	v_rcp_f32_e32 v72, v72
	s_nop 0
	v_mul_f32_e32 v72, v77, v72
	v_mul_f32_e32 v71, v71, v72
	v_cvt_pk_bf16_f32 v73, v70, v71
	ds_read_b32 v70, v235
	v_cvt_pk_bf16_f32 v72, v66, v67
	s_waitcnt lgkmcnt(0)
	v_and_b32_e32 v66, 15, v70
	v_lshl_add_u32 v249, v66, 10, v248
	v_lshlrev_b32_e32 v146, 2, v66
	v_lshl_add_u64 v[66:67], s[68:69], 0, v[146:147]
	v_lshl_add_u64 v[66:67], v[66:67], 0, v[114:115]
	ds_read_b128 v[110:113], v249
	ds_read_b128 v[252:255], v249 offset:512
	v_and_b32_e32 v71, 16, v70
	v_cmp_eq_u32_e32 vcc, 0, v71
	v_and_b32_e32 v70, 32, v70
	v_cmp_eq_u32_e64 s[0:1], 0, v70
	v_cndmask_b32_e64 v70, v186, 0, vcc
	v_cndmask_b32_e64 v71, v187, 0, vcc
	v_cndmask_b32_e64 v86, v188, 0, vcc
	v_cndmask_b32_e64 v87, v189, 0, vcc
	v_cndmask_b32_e64 v76, v194, 0, s[0:1]
	v_cndmask_b32_e64 v77, v195, 0, s[0:1]
	v_cndmask_b32_e64 v118, v196, 0, s[0:1]
	v_cndmask_b32_e64 v119, v197, 0, s[0:1]
	v_cndmask_b32_e64 v120, v200, 0, s[0:1]
	v_cndmask_b32_e64 v121, v201, 0, s[0:1]
	s_waitcnt lgkmcnt(0)
	v_pk_fma_f32 v[112:113], v[36:37], v[108:109], v[112:113]
	v_pk_fma_f32 v[110:111], v[34:35], v[106:107], v[110:111]
	v_pk_fma_f32 v[86:87], v[104:105], v[86:87], v[112:113]
	v_pk_fma_f32 v[70:71], v[102:103], v[70:71], v[110:111]
	v_mov_b64_e32 v[110:111], v[252:253]
	v_mov_b64_e32 v[112:113], v[254:255]
	v_cndmask_b32_e64 v66, v190, 0, vcc
	v_cndmask_b32_e64 v67, v191, 0, vcc
	v_pk_fma_f32 v[70:71], v[98:99], v[76:77], v[70:71]
	v_cndmask_b32_e64 v76, v198, 0, s[0:1]
	v_cndmask_b32_e64 v77, v199, 0, s[0:1]
	v_pk_fma_f32 v[86:87], v[100:101], v[118:119], v[86:87]
	v_cndmask_b32_e64 v118, v192, 0, vcc
	v_cndmask_b32_e64 v119, v193, 0, vcc
	s_nop 0
	v_pk_fma_f32 v[110:111], v[38:39], v[94:95], v[110:111]
	s_nop 0
	v_pk_fma_f32 v[66:67], v[90:91], v[66:67], v[110:111]
	v_pk_fma_f32 v[112:113], v[40:41], v[96:97], v[112:113]
	v_pk_fma_f32 v[66:67], v[80:81], v[76:77], v[66:67]
	v_mul_f32_e32 v76, 0xbfb8aa3b, v70
	v_exp_f32_e32 v76, v76
	v_pk_fma_f32 v[110:111], v[92:93], v[118:119], v[112:113]
	v_add_f32_e32 v76, 1.0, v76
	v_rcp_f32_e32 v76, v76
	v_pk_fma_f32 v[110:111], v[82:83], v[120:121], v[110:111]
	v_mul_f32_e32 v70, v70, v76
	v_mul_f32_e32 v66, v66, v70
	v_mul_f32_e32 v70, 0xbfb8aa3b, v71
	v_exp_f32_e32 v70, v70
	ds_read_b32 v76, v237
	v_add_f32_e32 v70, 1.0, v70
	v_rcp_f32_e32 v70, v70
	s_waitcnt lgkmcnt(0)
	v_and_b32_e32 v77, 16, v76
	v_cmp_eq_u32_e32 vcc, 0, v77
	v_mul_f32_e32 v70, v71, v70
	v_mul_f32_e32 v67, v67, v70
	v_mul_f32_e32 v70, 0xbfb8aa3b, v86
	v_exp_f32_e32 v70, v70
	v_mul_f32_e32 v71, 0xbfb8aa3b, v87
	v_exp_f32_e32 v71, v71
	v_cvt_pk_bf16_f32 v66, v66, v67
	v_add_f32_e32 v70, 1.0, v70
	v_rcp_f32_e32 v70, v70
	v_add_f32_e32 v71, 1.0, v71
	v_rcp_f32_e32 v71, v71
	v_cndmask_b32_e64 v77, v35, 0, vcc
	v_mul_f32_e32 v70, v86, v70
	v_mul_f32_e32 v70, v110, v70
	v_mul_f32_e32 v71, v87, v71
	v_mul_f32_e32 v71, v111, v71
	v_cvt_pk_bf16_f32 v67, v70, v71
	v_and_b32_e32 v70, 15, v76
	v_lshl_add_u32 v249, v70, 10, v248
	v_lshlrev_b32_e32 v146, 2, v70
	v_lshl_add_u64 v[70:71], s[68:69], 0, v[146:147]
	v_lshl_add_u64 v[70:71], v[70:71], 0, v[114:115]
	ds_read_b128 v[110:113], v249
	ds_read_b128 v[252:255], v249 offset:512
	v_and_b32_e32 v76, 32, v76
	v_cmp_eq_u32_e64 s[64:65], 0, v76
	v_cndmask_b32_e64 v76, v34, 0, vcc
	v_cndmask_b32_e64 v114, v36, 0, vcc
	v_cndmask_b32_e64 v115, v37, 0, vcc
	v_cndmask_b32_e64 v86, v186, 0, s[64:65]
	v_cndmask_b32_e64 v87, v187, 0, s[64:65]
	v_cndmask_b32_e64 v118, v188, 0, s[64:65]
	v_cndmask_b32_e64 v119, v189, 0, s[64:65]
	s_waitcnt lgkmcnt(0)
	v_pk_fma_f32 v[108:109], v[44:45], v[108:109], v[112:113]
	v_pk_fma_f32 v[106:107], v[42:43], v[106:107], v[110:111]
	s_nop 0
	v_pk_fma_f32 v[76:77], v[102:103], v[76:77], v[106:107]
	v_pk_fma_f32 v[102:103], v[104:105], v[114:115], v[108:109]
	v_pk_fma_f32 v[76:77], v[98:99], v[86:87], v[76:77]
	v_pk_fma_f32 v[102:103], v[100:101], v[118:119], v[102:103]
	v_mov_b64_e32 v[98:99], v[252:253]
	v_mov_b64_e32 v[100:101], v[254:255]
	v_cndmask_b32_e64 v70, v38, 0, vcc
	v_cndmask_b32_e64 v71, v39, 0, vcc
	v_cndmask_b32_e64 v86, v190, 0, s[64:65]
	v_cndmask_b32_e64 v87, v191, 0, s[64:65]
	v_cndmask_b32_e64 v104, v40, 0, vcc
	v_cndmask_b32_e64 v105, v41, 0, vcc
	v_cndmask_b32_e64 v106, v192, 0, s[64:65]
	v_cndmask_b32_e64 v107, v193, 0, s[64:65]
	s_and_b64 vcc, exec, s[60:61]
	s_nop 0
	v_pk_fma_f32 v[94:95], v[46:47], v[94:95], v[98:99]
	s_nop 0
	v_pk_fma_f32 v[70:71], v[90:91], v[70:71], v[94:95]
	v_pk_fma_f32 v[96:97], v[48:49], v[96:97], v[100:101]
	v_pk_fma_f32 v[70:71], v[80:81], v[86:87], v[70:71]
	v_mul_f32_e32 v80, 0xbfb8aa3b, v76
	v_exp_f32_e32 v80, v80
	v_pk_fma_f32 v[90:91], v[92:93], v[104:105], v[96:97]
	v_add_f32_e32 v80, 1.0, v80
	v_rcp_f32_e32 v80, v80
	v_pk_fma_f32 v[82:83], v[82:83], v[106:107], v[90:91]
	v_mul_f32_e32 v76, v76, v80
	v_mul_f32_e32 v70, v70, v76
	v_mul_f32_e32 v76, 0xbfb8aa3b, v77
	v_exp_f32_e32 v76, v76
	s_nop 0
	v_add_f32_e32 v76, 1.0, v76
	v_rcp_f32_e32 v76, v76
	s_nop 0
	v_mul_f32_e32 v76, v77, v76
	v_mul_f32_e32 v71, v71, v76
	v_mul_f32_e32 v76, 0xbfb8aa3b, v102
	v_exp_f32_e32 v76, v76
	v_mul_f32_e32 v77, 0xbfb8aa3b, v103
	v_exp_f32_e32 v77, v77
	v_add_f32_e32 v76, 1.0, v76
	v_rcp_f32_e32 v76, v76
	v_add_f32_e32 v77, 1.0, v77
	v_rcp_f32_e32 v77, v77
	v_mul_f32_e32 v76, v102, v76
	v_mul_f32_e32 v76, v82, v76
	v_cvt_pk_bf16_f32 v82, v70, v71
	v_or_b32_e32 v70, 4, v184
	v_mul_f32_e32 v77, v103, v77
	v_ashrrev_i32_e32 v71, 31, v70
	v_mul_f32_e32 v77, v83, v77
	v_lshlrev_b64 v[70:71], 2, v[70:71]
	v_cvt_pk_bf16_f32 v83, v76, v77
	v_lshl_add_u64 v[76:77], s[4:5], 0, v[70:71]
	global_load_dwordx4 v[104:107], v[76:77], off
	v_lshl_add_u64 v[76:77], s[96:97], 0, v[70:71]
	v_lshl_add_u64 v[70:71], s[78:79], 0, v[70:71]
	global_load_dwordx4 v[108:111], v[76:77], off
	global_load_dwordx4 v[112:115], v[70:71], off
	v_or_b32_e32 v70, 0x84, v184
	v_ashrrev_i32_e32 v71, 31, v70
	v_lshlrev_b64 v[70:71], 2, v[70:71]
	v_lshl_add_u64 v[76:77], s[4:5], 0, v[70:71]
	global_load_dwordx4 v[92:95], v[76:77], off
	v_lshl_add_u64 v[76:77], s[96:97], 0, v[70:71]
	v_lshl_add_u64 v[70:71], s[78:79], 0, v[70:71]
	global_load_dwordx4 v[96:99], v[76:77], off
	global_load_dwordx4 v[100:103], v[70:71], off
	s_cbranch_vccnz .LBB0_1204
	ds_read_b128 v[124:127], v221 offset:16
	ds_read_b128 v[128:131], v222 offset:16

.LBB0_1206:
	ds_read_b32 v243, v223
	s_waitcnt lgkmcnt(2)
	v_mov_b32_dpp v120, v26 row_shr:1 row_mask:0xf bank_mask:0xf
	v_mov_b32_dpp v121, v27 row_shr:1 row_mask:0xf bank_mask:0xf
	s_waitcnt lgkmcnt(1)
	v_mov_b32_dpp v116, v18 row_shr:1 row_mask:0xf bank_mask:0xf
	v_mov_b32_dpp v117, v19 row_shr:1 row_mask:0xf bank_mask:0xf
	s_waitcnt lgkmcnt(0)
	v_and_b32_e32 v70, 15, v243
	v_lshl_add_u32 v249, v70, 10, v248
	v_lshlrev_b32_e32 v146, 2, v70
	v_lshl_add_u64 v[70:71], s[68:69], 0, v[146:147]
	v_lshl_add_u64 v[70:71], v[184:185], 2, v[70:71]
	ds_read_b128 v[244:247], v249 offset:16
	ds_read_b128 v[252:255], v249 offset:528
	v_and_b32_e32 v76, 16, v243
	v_cmp_eq_u32_e32 vcc, 0, v76
	v_and_b32_e32 v76, 32, v243
	v_cmp_eq_u32_e64 s[0:1], 0, v76
	v_cndmask_b32_e64 v76, v124, 0, vcc
	v_cndmask_b32_e64 v77, v125, 0, vcc
	v_cndmask_b32_e64 v80, v128, 0, s[0:1]
	v_cndmask_b32_e64 v81, v129, 0, s[0:1]
	v_cndmask_b32_e64 v86, v126, 0, vcc
	v_cndmask_b32_e64 v90, v130, 0, s[0:1]
	v_cndmask_b32_e64 v87, v127, 0, vcc
	v_cndmask_b32_e64 v91, v131, 0, s[0:1]
	v_mov_b32_dpp v122, v28 row_shr:1 row_mask:0xf bank_mask:0xf
	v_mov_b32_dpp v118, v20 row_shr:1 row_mask:0xf bank_mask:0xf
	v_mov_b32_dpp v123, v29 row_shr:1 row_mask:0xf bank_mask:0xf
	v_mov_b32_dpp v119, v21 row_shr:1 row_mask:0xf bank_mask:0xf
	s_waitcnt vmcnt(0) lgkmcnt(0)
	v_pk_fma_f32 v[128:129], v[182:183], v[114:115], v[246:247]
	v_pk_fma_f32 v[130:131], v[178:179], v[112:113], v[244:245]
	v_pk_fma_f32 v[86:87], v[110:111], v[86:87], v[128:129]
	v_pk_fma_f32 v[76:77], v[108:109], v[76:77], v[130:131]
	v_mov_b64_e32 v[128:129], v[252:253]
	v_mov_b64_e32 v[130:131], v[254:255]
	v_cndmask_b32_e64 v70, v120, 0, vcc
	v_cndmask_b32_e64 v71, v121, 0, vcc
	v_pk_fma_f32 v[76:77], v[104:105], v[80:81], v[76:77]
	v_cndmask_b32_e64 v80, v116, 0, s[0:1]
	v_cndmask_b32_e64 v81, v117, 0, s[0:1]
	v_pk_fma_f32 v[86:87], v[106:107], v[90:91], v[86:87]
	v_cndmask_b32_e64 v90, v122, 0, vcc
	v_cndmask_b32_e64 v116, v118, 0, s[0:1]
	v_cndmask_b32_e64 v91, v123, 0, vcc
	v_cndmask_b32_e64 v117, v119, 0, s[0:1]
	s_nop 0
	v_pk_fma_f32 v[128:129], v[176:177], v[100:101], v[128:129]
	s_nop 0
	v_pk_fma_f32 v[70:71], v[96:97], v[70:71], v[128:129]
	v_pk_fma_f32 v[118:119], v[180:181], v[102:103], v[130:131]
	v_pk_fma_f32 v[70:71], v[92:93], v[80:81], v[70:71]
	v_mul_f32_e32 v80, 0xbfb8aa3b, v76
	v_exp_f32_e32 v80, v80
	v_pk_fma_f32 v[90:91], v[98:99], v[90:91], v[118:119]
	v_add_f32_e32 v80, 1.0, v80
	v_rcp_f32_e32 v80, v80
	v_pk_fma_f32 v[90:91], v[94:95], v[116:117], v[90:91]
	v_mul_f32_e32 v76, v76, v80
	v_mul_f32_e32 v70, v70, v76
	v_mul_f32_e32 v76, 0xbfb8aa3b, v77
	v_exp_f32_e32 v76, v76
	s_nop 0
	v_add_f32_e32 v76, 1.0, v76
	v_rcp_f32_e32 v76, v76
	s_nop 0
	v_mul_f32_e32 v76, v77, v76
	v_mul_f32_e32 v71, v71, v76
	v_mul_f32_e32 v76, 0xbfb8aa3b, v86
	v_exp_f32_e32 v76, v76
	v_mul_f32_e32 v77, 0xbfb8aa3b, v87
	v_exp_f32_e32 v77, v77
	v_add_f32_e32 v76, 1.0, v76
	v_rcp_f32_e32 v76, v76
	v_add_f32_e32 v77, 1.0, v77
	v_rcp_f32_e32 v77, v77
	v_mul_f32_e32 v76, v86, v76
	v_cvt_pk_bf16_f32 v86, v70, v71
	v_and_b32_e32 v70, 64, v243
	v_mul_f32_e32 v77, v87, v77
	v_cmp_ne_u32_e32 vcc, 0, v70
	v_mul_f32_e32 v76, v90, v76
	v_mul_f32_e32 v77, v91, v77
	v_cvt_pk_bf16_f32 v87, v76, v77
	s_and_saveexec_b64 s[0:1], vcc
	s_cbranch_execz .LBB0_1208
	v_add_u32_e32 v76, s17, v220
	v_mov_b64_e32 v[70:71], s[70:71]
	v_mad_i64_i32 v[70:71], s[38:39], v76, s34, v[70:71]
	s_lshl_b32 s38, s72, 7
	s_ashr_i32 s39, s38, 31
	v_lshl_add_u64 v[70:71], s[38:39], 1, v[70:71]
	v_lshlrev_b32_e32 v146, 1, v148
	v_lshl_add_u64 v[70:71], v[70:71], 0, v[146:147]
	global_store_dwordx4 v[70:71], v[84:87], off
.LBB0_1208:
	s_or_b64 exec, exec, s[0:1]
	ds_read_b32 v128, v225
	s_waitcnt lgkmcnt(0)
	v_and_b32_e32 v70, 15, v128
	v_lshl_add_u32 v249, v70, 10, v248
	v_lshlrev_b32_e32 v146, 2, v70
	v_lshl_add_u64 v[70:71], s[68:69], 0, v[146:147]
	v_lshl_add_u64 v[70:71], v[184:185], 2, v[70:71]
	ds_read_b128 v[84:87], v249 offset:16
	ds_read_b128 v[252:255], v249 offset:528
	v_and_b32_e32 v76, 16, v128
	v_cmp_eq_u32_e32 vcc, 0, v76
	v_and_b32_e32 v76, 32, v128
	v_cmp_eq_u32_e64 s[0:1], 0, v76
	v_cndmask_b32_e64 v90, v182, 0, vcc
	v_cndmask_b32_e64 v91, v183, 0, vcc
	v_cndmask_b32_e64 v76, v178, 0, vcc
	v_cndmask_b32_e64 v77, v179, 0, vcc
	v_cndmask_b32_e64 v116, v126, 0, s[0:1]
	v_cndmask_b32_e64 v117, v127, 0, s[0:1]
	v_cndmask_b32_e64 v80, v124, 0, s[0:1]
	v_cndmask_b32_e64 v81, v125, 0, s[0:1]
	v_cndmask_b32_e64 v118, v122, 0, s[0:1]
	v_cndmask_b32_e64 v119, v123, 0, s[0:1]
	s_waitcnt lgkmcnt(0)
	v_pk_fma_f32 v[86:87], v[174:175], v[114:115], v[86:87]
	v_pk_fma_f32 v[84:85], v[172:173], v[112:113], v[84:85]
	v_pk_fma_f32 v[86:87], v[110:111], v[90:91], v[86:87]
	v_pk_fma_f32 v[76:77], v[108:109], v[76:77], v[84:85]
	v_pk_fma_f32 v[90:91], v[106:107], v[116:117], v[86:87]
	v_mov_b64_e32 v[84:85], v[252:253]
	v_mov_b64_e32 v[86:87], v[254:255]
	v_cndmask_b32_e64 v70, v176, 0, vcc
	v_cndmask_b32_e64 v71, v177, 0, vcc
	v_pk_fma_f32 v[76:77], v[104:105], v[80:81], v[76:77]
	v_cndmask_b32_e64 v80, v120, 0, s[0:1]
	v_cndmask_b32_e64 v81, v121, 0, s[0:1]
	v_cndmask_b32_e64 v116, v180, 0, vcc
	v_cndmask_b32_e64 v117, v181, 0, vcc
	s_nop 0
	v_pk_fma_f32 v[84:85], v[168:169], v[100:101], v[84:85]
	s_nop 0
	v_pk_fma_f32 v[70:71], v[96:97], v[70:71], v[84:85]
	v_pk_fma_f32 v[86:87], v[170:171], v[102:103], v[86:87]
	v_pk_fma_f32 v[70:71], v[92:93], v[80:81], v[70:71]
	v_mul_f32_e32 v80, 0xbfb8aa3b, v76
	v_exp_f32_e32 v80, v80
	v_pk_fma_f32 v[86:87], v[98:99], v[116:117], v[86:87]
	v_add_f32_e32 v80, 1.0, v80
	v_rcp_f32_e32 v80, v80
	v_pk_fma_f32 v[84:85], v[94:95], v[118:119], v[86:87]
	v_mul_f32_e32 v76, v76, v80
	v_mul_f32_e32 v70, v70, v76
	v_mul_f32_e32 v76, 0xbfb8aa3b, v77
	v_exp_f32_e32 v76, v76
	s_nop 0
	v_add_f32_e32 v76, 1.0, v76
	v_rcp_f32_e32 v76, v76
	s_nop 0
	v_mul_f32_e32 v76, v77, v76
	v_mul_f32_e32 v71, v71, v76
	v_mul_f32_e32 v76, 0xbfb8aa3b, v90
	v_exp_f32_e32 v76, v76
	s_nop 0
	v_add_f32_e32 v76, 1.0, v76
	v_rcp_f32_e32 v76, v76
	s_nop 0
	v_mul_f32_e32 v76, v90, v76
	v_mul_f32_e32 v77, v84, v76
	v_mul_f32_e32 v76, 0xbfb8aa3b, v91
	v_exp_f32_e32 v76, v76
	s_nop 0
	v_add_f32_e32 v76, 1.0, v76
	v_rcp_f32_e32 v76, v76
	s_nop 0
	v_mul_f32_e32 v76, v91, v76
	v_mul_f32_e32 v80, v85, v76
	v_cvt_pk_bf16_f32 v76, v70, v71
	v_and_b32_e32 v70, 64, v128
	v_cmp_ne_u32_e32 vcc, 0, v70
	v_cvt_pk_bf16_f32 v77, v77, v80
	s_and_saveexec_b64 s[0:1], vcc
	s_cbranch_execz .LBB0_1210
	v_add_u32_e32 v80, s17, v224
	v_mov_b64_e32 v[70:71], s[70:71]
	v_mad_i64_i32 v[70:71], s[38:39], v80, s34, v[70:71]
	s_lshl_b32 s38, s72, 7
	s_ashr_i32 s39, s38, 31
	v_lshl_add_u64 v[70:71], s[38:39], 1, v[70:71]
	v_lshlrev_b32_e32 v146, 1, v148
	v_lshl_add_u64 v[70:71], v[70:71], 0, v[146:147]
	global_store_dwordx4 v[70:71], v[74:77], off
.LBB0_1210:
	s_or_b64 exec, exec, s[0:1]
	ds_read_b32 v118, v227
	s_waitcnt lgkmcnt(0)
	v_and_b32_e32 v70, 15, v118
	v_lshl_add_u32 v249, v70, 10, v248
	v_lshlrev_b32_e32 v146, 2, v70
	v_lshl_add_u64 v[70:71], s[68:69], 0, v[146:147]
	v_and_b32_e32 v74, 16, v118
	v_lshl_add_u64 v[70:71], v[184:185], 2, v[70:71]
	v_cmp_eq_u32_e32 vcc, 0, v74
	v_and_b32_e32 v74, 32, v118
	v_cmp_eq_u32_e64 s[0:1], 0, v74
	ds_read_b128 v[74:77], v249 offset:16
	ds_read_b128 v[252:255], v249 offset:528
	v_cndmask_b32_e64 v80, v172, 0, vcc
	v_cndmask_b32_e64 v81, v173, 0, vcc
	v_cndmask_b32_e64 v86, v174, 0, vcc
	v_cndmask_b32_e64 v87, v175, 0, vcc
	v_cndmask_b32_e64 v84, v178, 0, s[0:1]
	v_cndmask_b32_e64 v85, v179, 0, s[0:1]
	v_cndmask_b32_e64 v90, v182, 0, s[0:1]
	v_cndmask_b32_e64 v91, v183, 0, s[0:1]
	v_cndmask_b32_e64 v116, v180, 0, s[0:1]
	v_cndmask_b32_e64 v117, v181, 0, s[0:1]
	s_waitcnt lgkmcnt(0)
	v_pk_fma_f32 v[76:77], v[24:25], v[114:115], v[76:77]
	v_pk_fma_f32 v[74:75], v[22:23], v[112:113], v[74:75]
	v_pk_fma_f32 v[76:77], v[110:111], v[86:87], v[76:77]
	v_pk_fma_f32 v[74:75], v[108:109], v[80:81], v[74:75]
	v_pk_fma_f32 v[80:81], v[106:107], v[90:91], v[76:77]
	v_pk_fma_f32 v[84:85], v[104:105], v[84:85], v[74:75]
	v_mov_b64_e32 v[74:75], v[252:253]
	v_mov_b64_e32 v[76:77], v[254:255]
	v_cndmask_b32_e64 v90, v170, 0, vcc
	v_cndmask_b32_e64 v91, v171, 0, vcc
	v_cndmask_b32_e64 v70, v168, 0, vcc
	v_cndmask_b32_e64 v71, v169, 0, vcc
	v_cndmask_b32_e64 v86, v176, 0, s[0:1]
	v_cndmask_b32_e64 v87, v177, 0, s[0:1]
	s_nop 0
	v_pk_fma_f32 v[76:77], v[20:21], v[102:103], v[76:77]
	v_pk_fma_f32 v[74:75], v[18:19], v[100:101], v[74:75]
	v_pk_fma_f32 v[76:77], v[98:99], v[90:91], v[76:77]
	v_pk_fma_f32 v[70:71], v[96:97], v[70:71], v[74:75]
	v_pk_fma_f32 v[74:75], v[94:95], v[116:117], v[76:77]
	v_mul_f32_e32 v76, 0xbfb8aa3b, v84
	v_exp_f32_e32 v76, v76
	v_pk_fma_f32 v[70:71], v[92:93], v[86:87], v[70:71]
	v_add_f32_e32 v76, 1.0, v76
	v_rcp_f32_e32 v76, v76
	s_nop 0
	v_mul_f32_e32 v76, v84, v76
	v_mul_f32_e32 v70, v70, v76
	v_mul_f32_e32 v76, 0xbfb8aa3b, v85
	v_exp_f32_e32 v76, v76
	s_nop 0
	v_add_f32_e32 v76, 1.0, v76
	v_rcp_f32_e32 v76, v76
	s_nop 0
	v_mul_f32_e32 v76, v85, v76
	v_mul_f32_e32 v71, v71, v76
	v_mul_f32_e32 v76, 0xbfb8aa3b, v80
	v_exp_f32_e32 v76, v76
	v_cvt_pk_bf16_f32 v70, v70, v71
	s_nop 0
	v_add_f32_e32 v76, 1.0, v76
	v_rcp_f32_e32 v76, v76
	s_nop 0
	v_mul_f32_e32 v76, v80, v76
	v_mul_f32_e32 v74, v74, v76
	v_mul_f32_e32 v76, 0xbfb8aa3b, v81
	v_exp_f32_e32 v76, v76
	s_nop 0
	v_add_f32_e32 v76, 1.0, v76
	v_rcp_f32_e32 v76, v76
	s_nop 0
	v_mul_f32_e32 v76, v81, v76
	v_mul_f32_e32 v75, v75, v76
	v_cvt_pk_bf16_f32 v71, v74, v75
	v_and_b32_e32 v74, 64, v118
	v_cmp_ne_u32_e32 vcc, 0, v74
	s_and_saveexec_b64 s[0:1], vcc
	s_cbranch_execz .LBB0_1212
	v_add_u32_e32 v76, s17, v226
	v_mov_b64_e32 v[74:75], s[70:71]
	v_mad_i64_i32 v[74:75], s[38:39], v76, s34, v[74:75]
	s_lshl_b32 s38, s72, 7
	s_ashr_i32 s39, s38, 31
	v_lshl_add_u64 v[74:75], s[38:39], 1, v[74:75]
	v_lshlrev_b32_e32 v146, 1, v148
	v_lshl_add_u64 v[74:75], v[74:75], 0, v[146:147]
	global_store_dwordx4 v[74:75], v[68:71], off
.LBB0_1212:
	s_or_b64 exec, exec, s[0:1]
	ds_read_b32 v116, v229
	s_waitcnt lgkmcnt(0)
	v_and_b32_e32 v68, 15, v116
	v_lshl_add_u32 v249, v68, 10, v248
	v_lshlrev_b32_e32 v146, 2, v68
	v_lshl_add_u64 v[68:69], s[68:69], 0, v[146:147]
	v_lshl_add_u64 v[74:75], v[184:185], 2, v[68:69]
	v_and_b32_e32 v68, 16, v116
	v_cmp_eq_u32_e32 vcc, 0, v68
	v_and_b32_e32 v68, 32, v116
	v_cmp_eq_u32_e64 s[0:1], 0, v68
	ds_read_b128 v[68:71], v249 offset:16
	ds_read_b128 v[252:255], v249 offset:528
	v_cndmask_b32_e64 v76, v22, 0, vcc
	v_cndmask_b32_e64 v77, v23, 0, vcc
	v_cndmask_b32_e64 v84, v24, 0, vcc
	v_cndmask_b32_e64 v85, v25, 0, vcc
	v_cndmask_b32_e64 v80, v172, 0, s[0:1]
	v_cndmask_b32_e64 v81, v173, 0, s[0:1]
	v_cndmask_b32_e64 v86, v174, 0, s[0:1]
	v_cndmask_b32_e64 v87, v175, 0, s[0:1]
	v_cndmask_b32_e64 v90, v170, 0, s[0:1]
	v_cndmask_b32_e64 v91, v171, 0, s[0:1]
	s_waitcnt lgkmcnt(0)
	v_pk_fma_f32 v[70:71], v[32:33], v[114:115], v[70:71]
	v_pk_fma_f32 v[68:69], v[30:31], v[112:113], v[68:69]
	v_pk_fma_f32 v[70:71], v[110:111], v[84:85], v[70:71]
	v_pk_fma_f32 v[68:69], v[108:109], v[76:77], v[68:69]
	v_pk_fma_f32 v[76:77], v[106:107], v[86:87], v[70:71]
	v_pk_fma_f32 v[80:81], v[104:105], v[80:81], v[68:69]
	v_mov_b64_e32 v[68:69], v[252:253]
	v_mov_b64_e32 v[70:71], v[254:255]
	v_cndmask_b32_e64 v74, v18, 0, vcc
	v_cndmask_b32_e64 v75, v19, 0, vcc
	v_cndmask_b32_e64 v84, v168, 0, s[0:1]
	v_cndmask_b32_e64 v85, v169, 0, s[0:1]
	v_cndmask_b32_e64 v86, v20, 0, vcc
	v_cndmask_b32_e64 v87, v21, 0, vcc
	s_nop 0
	v_pk_fma_f32 v[68:69], v[26:27], v[100:101], v[68:69]
	s_nop 0
	v_pk_fma_f32 v[68:69], v[96:97], v[74:75], v[68:69]
	v_mul_f32_e32 v74, 0xbfb8aa3b, v80
	v_exp_f32_e32 v74, v74
	v_pk_fma_f32 v[68:69], v[92:93], v[84:85], v[68:69]
	v_pk_fma_f32 v[70:71], v[28:29], v[102:103], v[70:71]
	v_add_f32_e32 v74, 1.0, v74
	v_rcp_f32_e32 v74, v74
	v_pk_fma_f32 v[70:71], v[98:99], v[86:87], v[70:71]
	v_mul_f32_e32 v74, v80, v74
	v_mul_f32_e32 v68, v68, v74
	v_mul_f32_e32 v74, 0xbfb8aa3b, v81
	v_exp_f32_e32 v74, v74
	v_pk_fma_f32 v[70:71], v[94:95], v[90:91], v[70:71]
	v_add_f32_e32 v74, 1.0, v74
	v_rcp_f32_e32 v74, v74
	s_nop 0
	v_mul_f32_e32 v74, v81, v74
	v_mul_f32_e32 v69, v69, v74
	v_mul_f32_e32 v74, 0xbfb8aa3b, v76
	v_exp_f32_e32 v74, v74
	v_cvt_pk_bf16_f32 v90, v68, v69
	v_and_b32_e32 v68, 64, v116
	v_cmp_ne_u32_e32 vcc, 0, v68
	v_add_f32_e32 v74, 1.0, v74
	v_rcp_f32_e32 v74, v74
	s_nop 0
	v_mul_f32_e32 v74, v76, v74
	v_mul_f32_e32 v70, v70, v74
	v_mul_f32_e32 v74, 0xbfb8aa3b, v77
	v_exp_f32_e32 v74, v74
	s_nop 0
	v_add_f32_e32 v74, 1.0, v74
	v_rcp_f32_e32 v74, v74
	s_nop 0
	v_mul_f32_e32 v74, v77, v74
	v_mul_f32_e32 v71, v71, v74
	v_cvt_pk_bf16_f32 v91, v70, v71
	s_and_saveexec_b64 s[0:1], vcc
	s_cbranch_execz .LBB0_1214
	v_add_u32_e32 v70, s17, v228
	v_mov_b64_e32 v[68:69], s[70:71]
	v_mad_i64_i32 v[68:69], s[38:39], v70, s34, v[68:69]
	s_lshl_b32 s38, s72, 7
	s_ashr_i32 s39, s38, 31
	v_lshl_add_u64 v[68:69], s[38:39], 1, v[68:69]
	v_lshlrev_b32_e32 v146, 1, v148
	v_lshl_add_u64 v[68:69], v[68:69], 0, v[146:147]
	global_store_dwordx4 v[68:69], v[88:91], off

.LBB0_1218:
	ds_read_b32 v124, v231
	s_waitcnt lgkmcnt(2)
	v_mov_b32_dpp v68, v14 row_shr:1 row_mask:0xf bank_mask:0xf
	v_mov_b32_dpp v69, v15 row_shr:1 row_mask:0xf bank_mask:0xf
	s_waitcnt lgkmcnt(1)
	v_mov_b32_dpp v84, v2 row_shr:1 row_mask:0xf bank_mask:0xf
	v_mov_b32_dpp v85, v3 row_shr:1 row_mask:0xf bank_mask:0xf
	s_waitcnt lgkmcnt(0)
	v_and_b32_e32 v80, 15, v124
	v_lshl_add_u32 v249, v80, 10, v248
	v_lshlrev_b32_e32 v146, 2, v80
	v_lshl_add_u64 v[80:81], s[68:69], 0, v[146:147]
	v_and_b32_e32 v116, 16, v124
	v_lshl_add_u64 v[80:81], v[184:185], 2, v[80:81]
	v_cmp_eq_u32_e32 vcc, 0, v116
	v_and_b32_e32 v116, 32, v124
	v_cmp_eq_u32_e64 s[0:1], 0, v116
	ds_read_b128 v[116:119], v249 offset:16
	ds_read_b128 v[252:255], v249 offset:528
	v_cndmask_b32_e64 v120, v74, 0, vcc
	v_cndmask_b32_e64 v121, v75, 0, vcc
	v_cndmask_b32_e64 v122, v76, 0, vcc
	v_cndmask_b32_e64 v123, v77, 0, vcc
	v_cndmask_b32_e64 v88, v88, 0, s[0:1]
	v_cndmask_b32_e64 v89, v89, 0, s[0:1]
	v_cndmask_b32_e64 v90, v90, 0, s[0:1]
	v_cndmask_b32_e64 v91, v91, 0, s[0:1]
	v_cndmask_b32_e64 v84, v84, 0, s[0:1]
	v_cndmask_b32_e64 v85, v85, 0, s[0:1]
	v_mov_b32_dpp v70, v16 row_shr:1 row_mask:0xf bank_mask:0xf
	v_mov_b32_dpp v71, v17 row_shr:1 row_mask:0xf bank_mask:0xf
	v_mov_b32_dpp v86, v4 row_shr:1 row_mask:0xf bank_mask:0xf
	v_mov_b32_dpp v87, v5 row_shr:1 row_mask:0xf bank_mask:0xf
	v_cndmask_b32_e64 v86, v86, 0, s[0:1]
	v_cndmask_b32_e64 v87, v87, 0, s[0:1]
	s_waitcnt lgkmcnt(0)
	v_pk_fma_f32 v[118:119], v[166:167], v[114:115], v[118:119]
	v_pk_fma_f32 v[116:117], v[162:163], v[112:113], v[116:117]
	v_pk_fma_f32 v[118:119], v[110:111], v[122:123], v[118:119]
	v_pk_fma_f32 v[116:117], v[108:109], v[120:121], v[116:117]
	v_pk_fma_f32 v[118:119], v[106:107], v[90:91], v[118:119]
	v_pk_fma_f32 v[116:117], v[104:105], v[88:89], v[116:117]
	v_mov_b64_e32 v[88:89], v[252:253]
	v_mov_b64_e32 v[90:91], v[254:255]
	v_cndmask_b32_e64 v80, v68, 0, vcc
	v_cndmask_b32_e64 v81, v69, 0, vcc
	v_cndmask_b32_e64 v120, v70, 0, vcc
	v_cndmask_b32_e64 v121, v71, 0, vcc
	s_nop 0
	v_pk_fma_f32 v[88:89], v[160:161], v[100:101], v[88:89]
	s_nop 0
	v_pk_fma_f32 v[80:81], v[96:97], v[80:81], v[88:89]
	v_pk_fma_f32 v[90:91], v[164:165], v[102:103], v[90:91]
	v_pk_fma_f32 v[80:81], v[92:93], v[84:85], v[80:81]
	v_mul_f32_e32 v84, 0xbfb8aa3b, v116
	v_exp_f32_e32 v84, v84
	v_mul_f32_e32 v85, 0xbfb8aa3b, v119
	v_exp_f32_e32 v85, v85
	v_pk_fma_f32 v[88:89], v[98:99], v[120:121], v[90:91]
	v_add_f32_e32 v84, 1.0, v84
	v_rcp_f32_e32 v84, v84
	v_add_f32_e32 v85, 1.0, v85
	v_rcp_f32_e32 v85, v85
	v_pk_fma_f32 v[86:87], v[94:95], v[86:87], v[88:89]
	v_mul_f32_e32 v84, v116, v84
	v_mul_f32_e32 v80, v80, v84
	v_mul_f32_e32 v84, 0xbfb8aa3b, v117
	v_exp_f32_e32 v84, v84
	v_mul_f32_e32 v85, v119, v85
	v_mul_f32_e32 v85, v87, v85
	v_add_f32_e32 v84, 1.0, v84
	v_rcp_f32_e32 v84, v84
	s_nop 0
	v_mul_f32_e32 v84, v117, v84
	v_mul_f32_e32 v81, v81, v84
	v_mul_f32_e32 v84, 0xbfb8aa3b, v118
	v_exp_f32_e32 v84, v84
	v_cvt_pk_bf16_f32 v80, v80, v81
	s_nop 0
	v_add_f32_e32 v84, 1.0, v84
	v_rcp_f32_e32 v84, v84
	s_nop 0
	v_mul_f32_e32 v84, v118, v84
	v_mul_f32_e32 v84, v86, v84
	v_cvt_pk_bf16_f32 v81, v84, v85
	v_and_b32_e32 v84, 64, v124
	v_cmp_ne_u32_e32 vcc, 0, v84
	s_and_saveexec_b64 s[0:1], vcc
	s_cbranch_execz .LBB0_1220
	v_add_u32_e32 v86, s17, v230
	v_mov_b64_e32 v[84:85], s[70:71]
	v_mad_i64_i32 v[84:85], s[38:39], v86, s34, v[84:85]
	s_lshl_b32 s38, s72, 7
	s_ashr_i32 s39, s38, 31
	v_lshl_add_u64 v[84:85], s[38:39], 1, v[84:85]
	v_lshlrev_b32_e32 v146, 1, v148
	v_lshl_add_u64 v[84:85], v[84:85], 0, v[146:147]
	global_store_dwordx4 v[84:85], v[78:81], off
.LBB0_1220:
	s_or_b64 exec, exec, s[0:1]
	ds_read_b32 v90, v233
	s_waitcnt lgkmcnt(0)
	v_and_b32_e32 v78, 15, v90
	v_lshl_add_u32 v249, v78, 10, v248
	v_lshlrev_b32_e32 v146, 2, v78
	v_lshl_add_u64 v[78:79], s[68:69], 0, v[146:147]
	v_lshl_add_u64 v[84:85], v[184:185], 2, v[78:79]
	v_and_b32_e32 v78, 16, v90
	v_cmp_eq_u32_e32 vcc, 0, v78
	v_and_b32_e32 v78, 32, v90
	v_cmp_eq_u32_e64 s[0:1], 0, v78
	ds_read_b128 v[78:81], v249 offset:16
	ds_read_b128 v[252:255], v249 offset:528
	v_cndmask_b32_e64 v86, v162, 0, vcc
	v_cndmask_b32_e64 v87, v163, 0, vcc
	v_cndmask_b32_e64 v88, v166, 0, vcc
	v_cndmask_b32_e64 v89, v167, 0, vcc
	v_cndmask_b32_e64 v74, v74, 0, s[0:1]
	v_cndmask_b32_e64 v75, v75, 0, s[0:1]
	v_cndmask_b32_e64 v76, v76, 0, s[0:1]
	v_cndmask_b32_e64 v77, v77, 0, s[0:1]
	v_cndmask_b32_e64 v68, v68, 0, s[0:1]
	v_cndmask_b32_e64 v69, v69, 0, s[0:1]
	v_cndmask_b32_e64 v70, v70, 0, s[0:1]
	v_cndmask_b32_e64 v71, v71, 0, s[0:1]
	s_waitcnt lgkmcnt(0)
	v_pk_fma_f32 v[80:81], v[158:159], v[114:115], v[80:81]
	v_pk_fma_f32 v[78:79], v[136:137], v[112:113], v[78:79]
	v_pk_fma_f32 v[80:81], v[110:111], v[88:89], v[80:81]
	v_pk_fma_f32 v[78:79], v[108:109], v[86:87], v[78:79]
	v_pk_fma_f32 v[80:81], v[106:107], v[76:77], v[80:81]
	v_pk_fma_f32 v[78:79], v[104:105], v[74:75], v[78:79]
	v_mov_b64_e32 v[74:75], v[252:253]
	v_mov_b64_e32 v[76:77], v[254:255]
	v_cndmask_b32_e64 v84, v160, 0, vcc
	v_cndmask_b32_e64 v85, v161, 0, vcc
	v_cndmask_b32_e64 v86, v164, 0, vcc
	v_cndmask_b32_e64 v87, v165, 0, vcc
	s_nop 0
	v_pk_fma_f32 v[74:75], v[132:133], v[100:101], v[74:75]
	s_nop 0
	v_pk_fma_f32 v[74:75], v[96:97], v[84:85], v[74:75]
	v_pk_fma_f32 v[76:77], v[134:135], v[102:103], v[76:77]
	v_pk_fma_f32 v[68:69], v[92:93], v[68:69], v[74:75]
	v_mul_f32_e32 v74, 0xbfb8aa3b, v78
	v_exp_f32_e32 v74, v74
	v_pk_fma_f32 v[76:77], v[98:99], v[86:87], v[76:77]
	v_add_f32_e32 v74, 1.0, v74
	v_rcp_f32_e32 v74, v74
	v_pk_fma_f32 v[70:71], v[94:95], v[70:71], v[76:77]
	v_mul_f32_e32 v74, v78, v74
	v_mul_f32_e32 v68, v68, v74
	v_mul_f32_e32 v74, 0xbfb8aa3b, v79
	v_exp_f32_e32 v74, v74
	s_nop 0
	v_add_f32_e32 v74, 1.0, v74
	v_rcp_f32_e32 v74, v74
	s_nop 0
	v_mul_f32_e32 v74, v79, v74
	v_mul_f32_e32 v69, v69, v74
	v_mul_f32_e32 v74, 0xbfb8aa3b, v80
	v_exp_f32_e32 v74, v74
	s_nop 0
	v_add_f32_e32 v74, 1.0, v74
	v_rcp_f32_e32 v74, v74
	s_nop 0
	v_mul_f32_e32 v74, v80, v74
	v_mul_f32_e32 v70, v70, v74
	v_mul_f32_e32 v74, 0xbfb8aa3b, v81
	v_exp_f32_e32 v74, v74
	s_nop 0
	v_add_f32_e32 v74, 1.0, v74
	v_rcp_f32_e32 v74, v74
	s_nop 0
	v_mul_f32_e32 v74, v81, v74
	v_mul_f32_e32 v71, v71, v74
	v_cvt_pk_bf16_f32 v74, v68, v69
	v_and_b32_e32 v68, 64, v90
	v_cmp_ne_u32_e32 vcc, 0, v68
	v_cvt_pk_bf16_f32 v75, v70, v71
	s_and_saveexec_b64 s[0:1], vcc
	s_cbranch_execz .LBB0_1222
	v_add_u32_e32 v70, s17, v232
	v_mov_b64_e32 v[68:69], s[70:71]
	v_mad_i64_i32 v[68:69], s[38:39], v70, s34, v[68:69]
	s_lshl_b32 s38, s72, 7
	s_ashr_i32 s39, s38, 31
	v_lshl_add_u64 v[68:69], s[38:39], 1, v[68:69]
	v_lshlrev_b32_e32 v146, 1, v148
	v_lshl_add_u64 v[68:69], v[68:69], 0, v[146:147]
	global_store_dwordx4 v[68:69], v[72:75], off
.LBB0_1222:
	s_or_b64 exec, exec, s[0:1]
	ds_read_b32 v86, v235
	s_waitcnt lgkmcnt(0)
	v_and_b32_e32 v68, 15, v86
	v_lshl_add_u32 v249, v68, 10, v248
	v_lshlrev_b32_e32 v146, 2, v68
	v_lshl_add_u64 v[68:69], s[68:69], 0, v[146:147]
	v_lshl_add_u64 v[72:73], v[184:185], 2, v[68:69]
	v_and_b32_e32 v68, 16, v86
	v_cmp_eq_u32_e32 vcc, 0, v68
	v_and_b32_e32 v68, 32, v86
	v_cmp_eq_u32_e64 s[0:1], 0, v68
	ds_read_b128 v[68:71], v249 offset:16
	ds_read_b128 v[252:255], v249 offset:528
	v_cndmask_b32_e64 v74, v136, 0, vcc
	v_cndmask_b32_e64 v75, v137, 0, vcc
	v_cndmask_b32_e64 v78, v158, 0, vcc
	v_cndmask_b32_e64 v79, v159, 0, vcc
	v_cndmask_b32_e64 v76, v162, 0, s[0:1]
	v_cndmask_b32_e64 v77, v163, 0, s[0:1]
	v_cndmask_b32_e64 v80, v166, 0, s[0:1]
	v_cndmask_b32_e64 v81, v167, 0, s[0:1]
	v_cndmask_b32_e64 v84, v164, 0, s[0:1]
	v_cndmask_b32_e64 v85, v165, 0, s[0:1]
	s_waitcnt lgkmcnt(0)
	v_pk_fma_f32 v[70:71], v[8:9], v[114:115], v[70:71]
	v_pk_fma_f32 v[68:69], v[6:7], v[112:113], v[68:69]
	v_pk_fma_f32 v[70:71], v[110:111], v[78:79], v[70:71]
	v_pk_fma_f32 v[68:69], v[108:109], v[74:75], v[68:69]
	v_pk_fma_f32 v[74:75], v[106:107], v[80:81], v[70:71]
	v_pk_fma_f32 v[76:77], v[104:105], v[76:77], v[68:69]
	v_mov_b64_e32 v[68:69], v[252:253]
	v_mov_b64_e32 v[70:71], v[254:255]
	v_cndmask_b32_e64 v72, v132, 0, vcc
	v_cndmask_b32_e64 v73, v133, 0, vcc
	v_cndmask_b32_e64 v78, v160, 0, s[0:1]
	v_cndmask_b32_e64 v79, v161, 0, s[0:1]
	v_cndmask_b32_e64 v80, v134, 0, vcc
	v_cndmask_b32_e64 v81, v135, 0, vcc
	s_nop 0
	v_pk_fma_f32 v[68:69], v[2:3], v[100:101], v[68:69]
	s_nop 0
	v_pk_fma_f32 v[68:69], v[96:97], v[72:73], v[68:69]
	v_mul_f32_e32 v72, 0xbfb8aa3b, v76
	v_exp_f32_e32 v72, v72
	v_pk_fma_f32 v[68:69], v[92:93], v[78:79], v[68:69]
	v_pk_fma_f32 v[70:71], v[4:5], v[102:103], v[70:71]
	v_add_f32_e32 v72, 1.0, v72
	v_rcp_f32_e32 v72, v72
	v_pk_fma_f32 v[70:71], v[98:99], v[80:81], v[70:71]
	v_mul_f32_e32 v72, v76, v72
	v_mul_f32_e32 v68, v68, v72
	v_mul_f32_e32 v72, 0xbfb8aa3b, v77
	v_exp_f32_e32 v72, v72
	v_pk_fma_f32 v[70:71], v[94:95], v[84:85], v[70:71]
	v_add_f32_e32 v72, 1.0, v72
	v_rcp_f32_e32 v72, v72
	s_nop 0
	v_mul_f32_e32 v72, v77, v72
	v_mul_f32_e32 v69, v69, v72
	v_mul_f32_e32 v72, 0xbfb8aa3b, v74
	v_exp_f32_e32 v72, v72
	v_cvt_pk_bf16_f32 v68, v68, v69
	s_nop 0
	v_add_f32_e32 v72, 1.0, v72
	v_rcp_f32_e32 v72, v72
	s_nop 0
	v_mul_f32_e32 v72, v74, v72
	v_mul_f32_e32 v70, v70, v72
	v_mul_f32_e32 v72, 0xbfb8aa3b, v75
	v_exp_f32_e32 v72, v72
	s_nop 0
	v_add_f32_e32 v72, 1.0, v72
	v_rcp_f32_e32 v72, v72
	s_nop 0
	v_mul_f32_e32 v72, v75, v72
	v_mul_f32_e32 v71, v71, v72
	v_cvt_pk_bf16_f32 v69, v70, v71
	v_and_b32_e32 v70, 64, v86
	v_cmp_ne_u32_e32 vcc, 0, v70
	s_and_saveexec_b64 s[0:1], vcc
	s_cbranch_execz .LBB0_1224
	v_add_u32_e32 v72, s17, v234
	v_mov_b64_e32 v[70:71], s[70:71]
	v_mad_i64_i32 v[70:71], s[38:39], v72, s34, v[70:71]
	s_lshl_b32 s38, s72, 7
	s_ashr_i32 s39, s38, 31
	v_lshl_add_u64 v[70:71], s[38:39], 1, v[70:71]
	v_lshlrev_b32_e32 v146, 1, v148
	v_lshl_add_u64 v[70:71], v[70:71], 0, v[146:147]
	global_store_dwordx4 v[70:71], v[66:69], off
.LBB0_1224:
	s_or_b64 exec, exec, s[0:1]
	ds_read_b32 v86, v237
	s_waitcnt lgkmcnt(0)
	v_and_b32_e32 v66, 15, v86
	v_lshl_add_u32 v249, v66, 10, v248
	v_lshlrev_b32_e32 v146, 2, v66
	v_lshl_add_u64 v[66:67], s[68:69], 0, v[146:147]
	v_lshl_add_u64 v[70:71], v[184:185], 2, v[66:67]
	v_and_b32_e32 v66, 16, v86
	v_cmp_eq_u32_e32 vcc, 0, v66
	v_and_b32_e32 v66, 32, v86
	v_cmp_eq_u32_e64 s[0:1], 0, v66
	ds_read_b128 v[66:69], v249 offset:16
	ds_read_b128 v[252:255], v249 offset:528
	v_cndmask_b32_e64 v72, v6, 0, vcc
	v_cndmask_b32_e64 v73, v7, 0, vcc
	v_cndmask_b32_e64 v76, v8, 0, vcc
	v_cndmask_b32_e64 v77, v9, 0, vcc
	v_cndmask_b32_e64 v74, v136, 0, s[0:1]
	v_cndmask_b32_e64 v75, v137, 0, s[0:1]
	v_cndmask_b32_e64 v78, v158, 0, s[0:1]
	v_cndmask_b32_e64 v79, v159, 0, s[0:1]
	v_cndmask_b32_e64 v80, v134, 0, s[0:1]
	v_cndmask_b32_e64 v81, v135, 0, s[0:1]
	s_waitcnt lgkmcnt(0)
	v_pk_fma_f32 v[68:69], v[12:13], v[114:115], v[68:69]
	v_pk_fma_f32 v[66:67], v[10:11], v[112:113], v[66:67]
	v_pk_fma_f32 v[68:69], v[110:111], v[76:77], v[68:69]
	v_pk_fma_f32 v[66:67], v[108:109], v[72:73], v[66:67]
	v_pk_fma_f32 v[72:73], v[106:107], v[78:79], v[68:69]
	v_pk_fma_f32 v[74:75], v[104:105], v[74:75], v[66:67]
	v_mov_b64_e32 v[66:67], v[252:253]
	v_mov_b64_e32 v[68:69], v[254:255]
	v_cndmask_b32_e64 v70, v2, 0, vcc
	v_cndmask_b32_e64 v71, v3, 0, vcc
	v_cndmask_b32_e64 v76, v132, 0, s[0:1]
	v_cndmask_b32_e64 v77, v133, 0, s[0:1]
	v_cndmask_b32_e64 v78, v4, 0, vcc
	v_cndmask_b32_e64 v79, v5, 0, vcc
	s_nop 0
	v_pk_fma_f32 v[66:67], v[14:15], v[100:101], v[66:67]
	s_nop 0
	v_pk_fma_f32 v[66:67], v[96:97], v[70:71], v[66:67]
	v_mul_f32_e32 v70, 0xbfb8aa3b, v74
	v_exp_f32_e32 v70, v70
	v_pk_fma_f32 v[66:67], v[92:93], v[76:77], v[66:67]
	v_pk_fma_f32 v[68:69], v[16:17], v[102:103], v[68:69]
	v_add_f32_e32 v70, 1.0, v70
	v_rcp_f32_e32 v70, v70
	v_pk_fma_f32 v[68:69], v[98:99], v[78:79], v[68:69]
	v_mul_f32_e32 v70, v74, v70
	v_mul_f32_e32 v66, v66, v70
	v_mul_f32_e32 v70, 0xbfb8aa3b, v75
	v_exp_f32_e32 v70, v70
	v_pk_fma_f32 v[68:69], v[94:95], v[80:81], v[68:69]
	v_add_f32_e32 v70, 1.0, v70
	v_rcp_f32_e32 v70, v70
	s_nop 0
	v_mul_f32_e32 v70, v75, v70
	v_mul_f32_e32 v67, v67, v70
	v_mul_f32_e32 v70, 0xbfb8aa3b, v72
	v_exp_f32_e32 v70, v70
	v_cvt_pk_bf16_f32 v84, v66, v67
	v_and_b32_e32 v66, 64, v86
	v_cmp_ne_u32_e32 vcc, 0, v66
	v_add_f32_e32 v70, 1.0, v70
	v_rcp_f32_e32 v70, v70
	s_nop 0
	v_mul_f32_e32 v70, v72, v70
	v_mul_f32_e32 v68, v68, v70
	v_mul_f32_e32 v70, 0xbfb8aa3b, v73
	v_exp_f32_e32 v70, v70
	s_nop 0
	v_add_f32_e32 v70, 1.0, v70
	v_rcp_f32_e32 v70, v70
	s_nop 0
	v_mul_f32_e32 v70, v73, v70
	v_mul_f32_e32 v69, v69, v70
	v_cvt_pk_bf16_f32 v85, v68, v69
	s_and_saveexec_b64 s[0:1], vcc
	s_cbranch_execz .LBB0_1226
	v_add_u32_e32 v68, s17, v236
	v_mov_b64_e32 v[66:67], s[70:71]
	v_mad_i64_i32 v[66:67], s[38:39], v68, s34, v[66:67]
	s_lshl_b32 s38, s72, 7
	s_ashr_i32 s39, s38, 31
	v_lshl_add_u64 v[66:67], s[38:39], 1, v[66:67]
	v_lshlrev_b32_e32 v146, 1, v148
	v_lshl_add_u64 v[66:67], v[66:67], 0, v[146:147]
	global_store_dwordx4 v[66:67], v[82:85], off
.LBB0_1226:
	s_or_b64 exec, exec, s[0:1]
	s_barrier
	s_branch .LBB0_1193
.LBB0_1227:
	s_ashr_i32 s0, s17, 12
	s_mulk_i32 s0, 0x5800
	s_ashr_i32 s1, s0, 31
	s_add_u32 s0, s68, s0
	s_addc_u32 s1, s69, s1
	v_ashrrev_i32_e32 v185, 31, v184
	s_add_u32 s0, s0, 0x2c000
	v_lshlrev_b64 v[66:67], 2, v[184:185]
	s_addc_u32 s1, s1, 0
	v_lshl_add_u64 v[68:69], s[4:5], 0, v[66:67]
	v_lshl_add_u64 v[70:71], s[96:97], 0, v[66:67]
	global_load_dwordx4 v[72:75], v[68:69], off
	global_load_dwordx4 v[76:79], v[70:71], off
	v_lshl_add_u64 v[68:69], s[78:79], 0, v[66:67]
	v_lshl_add_u64 v[66:67], s[0:1], 0, v[66:67]
	global_load_dwordx4 v[80:83], v[68:69], off
	global_load_dwordx4 v[88:91], v[66:67], off
	v_or_b32_e32 v66, 0x80, v184
	v_ashrrev_i32_e32 v67, 31, v66
	v_lshlrev_b64 v[66:67], 2, v[66:67]
	v_lshl_add_u64 v[68:69], s[4:5], 0, v[66:67]
	v_lshl_add_u64 v[70:71], s[96:97], 0, v[66:67]
	global_load_dwordx4 v[84:87], v[68:69], off
	global_load_dwordx4 v[92:95], v[70:71], off
	v_lshl_add_u64 v[68:69], s[78:79], 0, v[66:67]
	v_lshl_add_u64 v[66:67], s[0:1], 0, v[66:67]
	global_load_dwordx4 v[96:99], v[68:69], off
	global_load_dwordx4 v[100:103], v[66:67], off
	v_mov_b32_e32 v108, 0
	s_and_b64 vcc, exec, s[60:61]
	v_mov_b32_e32 v112, 0
	v_mov_b32_e32 v113, 0
	v_mov_b32_e32 v114, 0
	v_mov_b32_e32 v115, 0
	v_mov_b32_e32 v66, 0
	v_mov_b32_e32 v67, 0
	v_mov_b32_e32 v68, 0
	v_mov_b32_e32 v69, 0
	s_cbranch_vccnz .LBB0_1229
	ds_read_b128 v[66:69], v221
	ds_read_b128 v[112:115], v222
